# scan_dir<0>: wave-uniform 'latent' mask built by one s_andn2_b64 instead of the v_cndmask + v_cmp ballot (strategy 7.12, ballot trimmed)
# speedup vs baseline: 1.0031x; 1.0027x over previous
; __device__ __forceinline__ float bf2f(bf16_t b) { return __uint_as_float(((unsigned)b) << 16); }
; __device__ __forceinline__ float fast_sigmoid(float x) { return __builtin_amdgcn_rcpf(1.0f + __builtin_amdgcn_exp2f(-1.4426950408889634f * x)); }
; template <int DIR>
; __device__ __forceinline__ void scan_dir(PP p, const bf16_t* xs, const ScanW& w, ScanW& wn, int ndir, int nct, bool do_next, int n, int ct, int l31, int hl, int id, int rowbase, bool latent, float (&hf)[2][16]) {
;     ...
;     for (int rt = 0; rt < 2; ++rt) {
;         bf16x8 af[4];
; #pragma unroll
;         for (int st = 0; st < 4; ++st) af[st] = *(const bf16x8*)(xs + (32 * rt + l31) * XS + 64 * n + 16 * st + 8 * hl);
;         f32x16 ga, gi;
; #pragma unroll
;         for (int i = 0; i < 16; ++i) { ga[i] = 0.f; gi[i] = 0.f; }
; #pragma unroll
;         for (int st = 0; st < 4; ++st) { ga = __builtin_amdgcn_mfma_f32_32x32x16_bf16(af[st], wfa[st], ga, 0, 0, 0); gi = __builtin_amdgcn_mfma_f32_32x32x16_bf16(af[st], wfi[st], gi, 0, 0, 0); }
; #pragma unroll
;         for (int i = 0; i < 16; ++i) {
;             const int token = 32 * rt + 8 * (i >> 2) + 4 * hl + (i & 3);
;             const float xv = bf2f(xs[token * XS + ch]);
;             const float rr = fast_sigmoid(ga[i] + ba), ii = fast_sigmoid(gi[i] + bi);
;             const float la2 = rr * sp8l2;
;             const float av = __builtin_amdgcn_exp2f(la2);
;             const float t2 = la2 * 1.3862943611f;
;             float em1p = t2 * (1.0f + t2 * (0.5f + t2 * (0.16666667f + t2 * (0.041666668f + t2 * 0.0083333333f)))), em1e = __builtin_fmaf(av, av, -1.0f);
;             asm volatile("" : "+v"(em1p), "+v"(em1e));
;             const float em1 = (t2 > -0.1f) ? em1p : em1e;
;             a[rt][i] = av; u[rt][i] = __builtin_amdgcn_sqrtf(-em1) * (ii * xv);
;         }
.Lscan_nomul1:
	v_mfma_f32_32x32x16_bf16 v[18:33], v[2:5], v[114:117], 0
	s_waitcnt vmcnt(2)
	v_mfma_f32_32x32x16_bf16 v[2:17], v[2:5], v[134:137], 0
	s_waitcnt lgkmcnt(1)
	v_mfma_f32_32x32x16_bf16 v[18:33], v[34:37], v[118:121], v[18:33]
	v_mfma_f32_32x32x16_bf16 v[2:17], v[34:37], v[126:129], v[2:17]
	ds_read_b128 v[34:37], v187 offset:96
	s_waitcnt lgkmcnt(1)
	v_mfma_f32_32x32x16_bf16 v[18:33], v[38:41], v[122:125], v[18:33]
	s_waitcnt vmcnt(1) lgkmcnt(0)
	ds_read_u16 v82, v0 offset:1040
	ds_read_u16 v83, v0 offset:2080
	ds_read_u16 v84, v0 offset:3120
	v_add_u32_e32 v113, v42, v152
	ds_read_u16 v85, v113
	ds_read_u16 v86, v0 offset:9360
	ds_read_u16 v87, v0 offset:10400
	ds_read_u16 v88, v0 offset:11440
	ds_read_u16 v89, v113 offset:8320
	ds_read_u16 v90, v0 offset:17680
	ds_read_u16 v91, v0 offset:18720
	ds_read_u16 v92, v0 offset:19760
	ds_read_u16 v93, v0 offset:34320
	ds_read_u16 v94, v0 offset:35360
	ds_read_u16 v95, v0 offset:36400
	ds_read_u16 v96, v0 offset:41600
	ds_read_u16 v97, v0 offset:42640
	ds_read_u16 v98, v0 offset:43680
	ds_read_u16 v99, v0 offset:44720
	ds_read_u16 v100, v0 offset:49920
	ds_read_u16 v101, v0 offset:50960
	ds_read_u16 v102, v0 offset:52000
	ds_read_u16 v103, v0 offset:53040
	ds_read_u16 v104, v0 offset:58240
	ds_read_u16 v105, v0 offset:59280
	ds_read_u16 v106, v0 offset:60320
	v_mfma_f32_32x32x16_bf16 v[18:33], v[34:37], v[138:141], v[18:33]
	v_mfma_f32_32x32x16_bf16 v[2:17], v[38:41], v[130:133], v[2:17]
	s_nop 10
	v_add_f32_e32 v18, v192, v18
	v_mul_f32_e32 v18, 0xbfb8aa3b, v18
	v_exp_f32_e32 v18, v18
	v_add_f32_e32 v19, v192, v19
	v_mul_f32_e32 v19, 0xbfb8aa3b, v19
	v_exp_f32_e32 v19, v19
	v_add_f32_e32 v18, 1.0, v18
	s_waitcnt vmcnt(0)
	v_mfma_f32_32x32x16_bf16 v[2:17], v[34:37], v[142:145], v[2:17]
	v_rcp_f32_e32 v18, v18
	v_add_f32_e32 v19, 1.0, v19
	v_rcp_f32_e32 v19, v19
	v_lshlrev_b32_e32 v34, 16, v43
	v_mul_f32_e32 v18, v194, v18
	v_exp_f32_e32 v50, v18
	v_mul_f32_e32 v18, 0x3fb17218, v18
	s_nop 4
	v_add_f32_e32 v2, v191, v2
	v_mul_f32_e32 v2, 0xbfb8aa3b, v2
	v_exp_f32_e32 v2, v2
	v_fmamk_f32 v35, v18, 0x3c088888, v186
	v_fmaak_f32 v35, v18, v35, 0x3e2aaaab
	v_fma_f32 v35, v18, v35, 0.5
	v_add_f32_e32 v2, 1.0, v2
	v_add_f32_e32 v3, v191, v3
	v_rcp_f32_e32 v2, v2
	v_fma_f32 v35, v18, v35, 1.0
	v_mul_f32_e32 v3, 0xbfb8aa3b, v3
	v_mul_f32_e32 v35, v18, v35
	v_fma_f32 v36, v50, v50, -1.0
	v_exp_f32_e32 v3, v3
	v_mul_f32_e32 v19, v194, v19
	v_cmp_lt_f32_e32 vcc, s76, v18
	v_exp_f32_e32 v52, v19
	v_mul_f32_e32 v19, 0x3fb17218, v19
	v_cndmask_b32_e32 v18, v36, v35, vcc
	v_fmamk_f32 v35, v19, 0x3c088888, v186
	v_mul_f32_e32 v2, v2, v34
	v_fmaak_f32 v35, v19, v35, 0x3e2aaaab
	v_sqrt_f32_e64 v18, -v18
	v_add_f32_e32 v3, 1.0, v3
	v_fma_f32 v35, v19, v35, 0.5
	v_add_f32_e32 v4, v191, v4
	v_rcp_f32_e32 v3, v3
	v_fma_f32 v35, v19, v35, 1.0
	v_mul_f32_e32 v4, 0xbfb8aa3b, v4
	v_mul_f32_e32 v35, v19, v35
	v_fma_f32 v36, v52, v52, -1.0
	v_cmp_lt_f32_e32 vcc, s76, v19
	v_exp_f32_e32 v4, v4
	v_mul_f32_e32 v2, v2, v18
	v_cndmask_b32_e32 v19, v36, v35, vcc
	v_sqrt_f32_e64 v19, -v19
	s_waitcnt lgkmcnt(0)
	v_lshlrev_b32_e32 v18, 16, v82
	v_mul_f32_e32 v3, v3, v18
	v_add_f32_e32 v4, 1.0, v4
	v_rcp_f32_e32 v4, v4
	v_mul_f32_e32 v3, v3, v19
	v_add_f32_e32 v19, v192, v20
	v_mul_f32_e32 v19, 0xbfb8aa3b, v19
	v_exp_f32_e32 v19, v19
	s_waitcnt lgkmcnt(0)
	v_lshlrev_b32_e32 v18, 16, v83
	v_mul_f32_e32 v4, v4, v18
	v_add_f32_e32 v18, v192, v21
	v_mul_f32_e32 v18, 0xbfb8aa3b, v18
	v_exp_f32_e32 v18, v18
	v_add_f32_e32 v19, 1.0, v19
	v_rcp_f32_e32 v19, v19
	v_add_f32_e32 v5, v191, v5
	v_add_f32_e32 v18, 1.0, v18
	v_rcp_f32_e32 v18, v18
	v_mul_f32_e32 v19, v194, v19
	v_exp_f32_e32 v51, v19
	v_mul_f32_e32 v19, 0x3fb17218, v19
	v_fmamk_f32 v20, v19, 0x3c088888, v186
	v_fmaak_f32 v20, v19, v20, 0x3e2aaaab
	v_mul_f32_e32 v18, v194, v18
	v_fma_f32 v20, v19, v20, 0.5
	v_mul_f32_e32 v5, 0xbfb8aa3b, v5
	v_exp_f32_e32 v54, v18
	v_mul_f32_e32 v18, 0x3fb17218, v18
	v_fma_f32 v20, v19, v20, 1.0
	v_exp_f32_e32 v5, v5
	v_fmamk_f32 v21, v18, 0x3c088888, v186
	v_mul_f32_e32 v20, v19, v20
	v_fma_f32 v34, v51, v51, -1.0
	v_fmaak_f32 v21, v18, v21, 0x3e2aaaab
	v_cmp_lt_f32_e32 vcc, s76, v19
	v_fma_f32 v21, v18, v21, 0.5
	v_fma_f32 v21, v18, v21, 1.0
	v_cndmask_b32_e32 v19, v34, v20, vcc
	v_sqrt_f32_e64 v19, -v19
	v_add_f32_e32 v5, 1.0, v5
	v_mul_f32_e32 v21, v18, v21
	v_fma_f32 v34, v54, v54, -1.0
	v_cmp_lt_f32_e32 vcc, s76, v18
	v_rcp_f32_e32 v5, v5
	v_add_f32_e32 v6, v191, v6
	v_cndmask_b32_e32 v18, v34, v21, vcc
	v_sqrt_f32_e64 v18, -v18
	v_mul_f32_e32 v6, 0xbfb8aa3b, v6
	v_mul_f32_e32 v4, v4, v19
	s_waitcnt lgkmcnt(0)
	v_lshlrev_b32_e32 v19, 16, v84
	v_exp_f32_e32 v6, v6
	v_mul_f32_e32 v5, v5, v19
	v_mul_f32_e32 v5, v18, v5
	v_add_u32_e32 v18, v42, v152
	v_add_f32_e32 v20, v192, v22
	v_mul_f32_e32 v20, 0xbfb8aa3b, v20
	v_add_f32_e32 v6, 1.0, v6
	v_exp_f32_e32 v20, v20
	v_rcp_f32_e32 v6, v6
	s_waitcnt lgkmcnt(0)
	v_lshlrev_b32_e32 v19, 16, v85
	v_add_f32_e32 v7, v191, v7
	v_add_f32_e32 v20, 1.0, v20
	v_mul_f32_e32 v6, v6, v19
	v_add_f32_e32 v19, v192, v23
	v_rcp_f32_e32 v20, v20
	v_mul_f32_e32 v19, 0xbfb8aa3b, v19
	v_exp_f32_e32 v19, v19
	v_mul_f32_e32 v7, 0xbfb8aa3b, v7
	v_mul_f32_e32 v20, v194, v20
	v_exp_f32_e32 v53, v20
	v_mul_f32_e32 v20, 0x3fb17218, v20
	v_add_f32_e32 v19, 1.0, v19
	v_fmamk_f32 v21, v20, 0x3c088888, v186
	v_rcp_f32_e32 v19, v19
	v_fmaak_f32 v21, v20, v21, 0x3e2aaaab
	v_fma_f32 v21, v20, v21, 0.5
	v_fma_f32 v21, v20, v21, 1.0
	v_mul_f32_e32 v21, v20, v21
	v_fma_f32 v22, v53, v53, -1.0
	v_mul_f32_e32 v19, v194, v19
	v_cmp_lt_f32_e32 vcc, s76, v20
	v_exp_f32_e32 v55, v19
	v_mul_f32_e32 v19, 0x3fb17218, v19
	v_cndmask_b32_e32 v20, v22, v21, vcc
	v_exp_f32_e32 v7, v7
	v_fmamk_f32 v22, v19, 0x3c088888, v186
	v_fmaak_f32 v22, v19, v22, 0x3e2aaaab
	v_fma_f32 v22, v19, v22, 0.5
	v_fma_f32 v22, v19, v22, 1.0
	v_sqrt_f32_e64 v20, -v20
	v_add_f32_e32 v7, 1.0, v7
	v_mul_f32_e32 v22, v19, v22
	v_fma_f32 v23, v55, v55, -1.0
	v_cmp_lt_f32_e32 vcc, s76, v19
	v_rcp_f32_e32 v7, v7
	v_add_f32_e32 v8, v191, v8
	v_cndmask_b32_e32 v19, v23, v22, vcc
	v_sqrt_f32_e64 v19, -v19
	v_mul_f32_e32 v8, 0xbfb8aa3b, v8
	v_exp_f32_e32 v8, v8
	v_mul_f32_e32 v6, v20, v6
	s_waitcnt lgkmcnt(0)
; __device__ __forceinline__ float bf2f(bf16_t b) { return __uint_as_float(((unsigned)b) << 16); }
; __device__ __forceinline__ float fast_sigmoid(float x) { return __builtin_amdgcn_rcpf(1.0f + __builtin_amdgcn_exp2f(-1.4426950408889634f * x)); }
; template <int DIR>
; __device__ __forceinline__ void scan_dir(PP p, const bf16_t* xs, const ScanW& w, ScanW& wn, int ndir, int nct, bool do_next, int n, int ct, int l31, int hl, int id, int rowbase, bool latent, float (&hf)[2][16]) {
;     ...
; #pragma unroll
;         for (int i = 0; i < 16; ++i) {
;             const int token = 32 * rt + 8 * (i >> 2) + 4 * hl + (i & 3);
;             const float xv = bf2f(xs[token * XS + ch]);
;             const float rr = fast_sigmoid(ga[i] + ba), ii = fast_sigmoid(gi[i] + bi);
;             const float la2 = rr * sp8l2;
;             const float av = __builtin_amdgcn_exp2f(la2);
;             const float t2 = la2 * 1.3862943611f;
;             float em1p = t2 * (1.0f + t2 * (0.5f + t2 * (0.16666667f + t2 * (0.041666668f + t2 * 0.0083333333f)))), em1e = __builtin_fmaf(av, av, -1.0f);
;             asm volatile("" : "+v"(em1p), "+v"(em1e));
;             const float em1 = (t2 > -0.1f) ? em1p : em1e;
;             a[rt][i] = av; u[rt][i] = __builtin_amdgcn_sqrtf(-em1) * (ii * xv);
;         }
	v_lshlrev_b32_e32 v20, 16, v86
	v_mul_f32_e32 v7, v7, v20
	v_mul_f32_e32 v7, v19, v7
	v_add_f32_e32 v20, v192, v24
	v_mul_f32_e32 v20, 0xbfb8aa3b, v20
	v_add_f32_e32 v8, 1.0, v8
	v_exp_f32_e32 v20, v20
	v_rcp_f32_e32 v8, v8
	s_waitcnt lgkmcnt(0)
	v_lshlrev_b32_e32 v19, 16, v87
	v_add_f32_e32 v9, v191, v9
	v_add_f32_e32 v20, 1.0, v20
	v_mul_f32_e32 v8, v8, v19
	v_add_f32_e32 v19, v192, v25
	v_rcp_f32_e32 v20, v20
	v_mul_f32_e32 v19, 0xbfb8aa3b, v19
	v_exp_f32_e32 v19, v19
	v_mul_f32_e32 v9, 0xbfb8aa3b, v9
	v_mul_f32_e32 v20, v194, v20
	v_exp_f32_e32 v67, v20
	v_mul_f32_e32 v20, 0x3fb17218, v20
	v_add_f32_e32 v19, 1.0, v19
	v_fmamk_f32 v21, v20, 0x3c088888, v186
	v_rcp_f32_e32 v19, v19
	v_fmaak_f32 v21, v20, v21, 0x3e2aaaab
	v_fma_f32 v21, v20, v21, 0.5
	v_fma_f32 v21, v20, v21, 1.0
	v_mul_f32_e32 v21, v20, v21
	v_fma_f32 v22, v67, v67, -1.0
	v_mul_f32_e32 v19, v194, v19
	v_cmp_lt_f32_e32 vcc, s76, v20
	v_exp_f32_e32 v69, v19
	v_mul_f32_e32 v19, 0x3fb17218, v19
	v_cndmask_b32_e32 v20, v22, v21, vcc
	v_exp_f32_e32 v9, v9
	v_fmamk_f32 v22, v19, 0x3c088888, v186
	v_fmaak_f32 v22, v19, v22, 0x3e2aaaab
	v_fma_f32 v22, v19, v22, 0.5
	v_fma_f32 v22, v19, v22, 1.0
	v_sqrt_f32_e64 v20, -v20
	v_add_f32_e32 v9, 1.0, v9
	v_mul_f32_e32 v22, v19, v22
	v_fma_f32 v23, v69, v69, -1.0
	v_cmp_lt_f32_e32 vcc, s76, v19
	v_rcp_f32_e32 v9, v9
	v_add_f32_e32 v10, v191, v10
	v_cndmask_b32_e32 v19, v23, v22, vcc
	v_sqrt_f32_e64 v19, -v19
	v_mul_f32_e32 v10, 0xbfb8aa3b, v10
	v_exp_f32_e32 v10, v10
	v_mul_f32_e32 v8, v20, v8
	s_waitcnt lgkmcnt(0)
	v_lshlrev_b32_e32 v20, 16, v88
	v_mul_f32_e32 v9, v9, v20
	v_mul_f32_e32 v76, v19, v9
	v_add_f32_e32 v19, v192, v26
	v_mul_f32_e32 v19, 0xbfb8aa3b, v19
	v_add_f32_e32 v10, 1.0, v10
	v_exp_f32_e32 v19, v19
	v_rcp_f32_e32 v10, v10
	s_waitcnt lgkmcnt(0)
	v_lshlrev_b32_e32 v9, 16, v89
	v_add_f32_e32 v11, v191, v11
	v_add_f32_e32 v19, 1.0, v19
	v_mul_f32_e32 v9, v10, v9
	v_add_f32_e32 v10, v192, v27
	v_rcp_f32_e32 v19, v19
	v_mul_f32_e32 v10, 0xbfb8aa3b, v10
	v_exp_f32_e32 v10, v10
	v_mul_f32_e32 v11, 0xbfb8aa3b, v11
	v_mul_f32_e32 v19, v194, v19
	v_exp_f32_e32 v68, v19
	v_mul_f32_e32 v19, 0x3fb17218, v19
	v_add_f32_e32 v10, 1.0, v10
	v_fmamk_f32 v20, v19, 0x3c088888, v186
	v_rcp_f32_e32 v10, v10
	v_fmaak_f32 v20, v19, v20, 0x3e2aaaab
	v_fma_f32 v20, v19, v20, 0.5
	v_fma_f32 v20, v19, v20, 1.0
	v_mul_f32_e32 v20, v19, v20
	v_fma_f32 v21, v68, v68, -1.0
	v_mul_f32_e32 v10, v194, v10
	v_cmp_lt_f32_e32 vcc, s76, v19
	v_exp_f32_e32 v71, v10
	v_mul_f32_e32 v10, 0x3fb17218, v10
	v_cndmask_b32_e32 v19, v21, v20, vcc
	v_exp_f32_e32 v11, v11
	v_fmamk_f32 v21, v10, 0x3c088888, v186
	v_fmaak_f32 v21, v10, v21, 0x3e2aaaab
	v_fma_f32 v21, v10, v21, 0.5
	v_fma_f32 v21, v10, v21, 1.0
	v_sqrt_f32_e64 v19, -v19
	v_add_f32_e32 v11, 1.0, v11
	v_mul_f32_e32 v21, v10, v21
	v_fma_f32 v22, v71, v71, -1.0
	v_cmp_lt_f32_e32 vcc, s76, v10
	v_rcp_f32_e32 v11, v11
	v_mul_f32_e32 v74, v19, v9
	v_cndmask_b32_e32 v10, v22, v21, vcc
	v_sqrt_f32_e64 v10, -v10
	s_waitcnt lgkmcnt(0)
	v_lshlrev_b32_e32 v9, 16, v90
	v_mul_f32_e32 v9, v11, v9
	v_add_f32_e32 v11, v191, v12
	v_mul_f32_e32 v73, v10, v9
	v_add_f32_e32 v10, v192, v28
	v_mul_f32_e32 v10, 0xbfb8aa3b, v10
	v_exp_f32_e32 v10, v10
	v_mul_f32_e32 v11, 0xbfb8aa3b, v11
	v_exp_f32_e32 v11, v11
	v_add_f32_e32 v10, 1.0, v10
	v_rcp_f32_e32 v10, v10
	s_waitcnt lgkmcnt(0)
	v_lshlrev_b32_e32 v9, 16, v91
	v_add_f32_e32 v11, 1.0, v11
	v_rcp_f32_e32 v11, v11
	v_mul_f32_e32 v10, v194, v10
	v_exp_f32_e32 v70, v10
	v_mul_f32_e32 v10, 0x3fb17218, v10
	v_fmamk_f32 v12, v10, 0x3c088888, v186
	v_fmaak_f32 v12, v10, v12, 0x3e2aaaab
	v_fma_f32 v12, v10, v12, 0.5
	v_fma_f32 v12, v10, v12, 1.0
	v_mul_f32_e32 v12, v10, v12
	v_fma_f32 v19, v70, v70, -1.0
	v_cmp_lt_f32_e32 vcc, s76, v10
	v_mul_f32_e32 v9, v11, v9
	v_add_f32_e32 v11, v191, v13
	v_cndmask_b32_e32 v10, v19, v12, vcc
	v_add_f32_e32 v12, v192, v29
	v_mul_f32_e32 v12, 0xbfb8aa3b, v12
	v_exp_f32_e32 v12, v12
	v_sqrt_f32_e64 v19, -v10
	v_mul_f32_e32 v11, 0xbfb8aa3b, v11
	v_exp_f32_e32 v21, v11
	v_add_f32_e32 v10, 1.0, v12
	v_rcp_f32_e32 v10, v10
	v_add_f32_e32 v11, v192, v30
	v_mul_f32_e32 v11, 0xbfb8aa3b, v11
	v_exp_f32_e32 v11, v11
	v_mul_f32_e32 v10, v194, v10
	v_mul_f32_e32 v22, 0x3fb17218, v10
	v_exp_f32_e32 v75, v10
	v_fmamk_f32 v10, v22, 0x3c088888, v186
	v_fmaak_f32 v10, v22, v10, 0x3e2aaaab
	v_fma_f32 v10, v22, v10, 0.5
	v_fma_f32 v10, v22, v10, 1.0
	v_mul_f32_e32 v23, v22, v10
	v_add_f32_e32 v10, 1.0, v11
	v_rcp_f32_e32 v10, v10
	v_add_f32_e32 v11, v192, v31
	v_mul_f32_e32 v11, 0xbfb8aa3b, v11
	v_exp_f32_e32 v11, v11
	v_mul_f32_e32 v10, v194, v10
	v_mul_f32_e32 v60, 0x3fb17218, v10
	v_exp_f32_e32 v72, v10
	v_fmamk_f32 v10, v60, 0x3c088888, v186
	v_fmaak_f32 v10, v60, v10, 0x3e2aaaab
	v_fma_f32 v10, v60, v10, 0.5
	v_fma_f32 v10, v60, v10, 1.0
	v_mul_f32_e32 v61, v60, v10
	v_add_f32_e32 v10, 1.0, v11
	v_rcp_f32_e32 v10, v10
	v_add_f32_e32 v11, v192, v32
	v_mul_f32_e32 v11, 0xbfb8aa3b, v11
	v_exp_f32_e32 v11, v11
	v_mul_f32_e32 v10, v194, v10
	v_mul_f32_e32 v64, 0x3fb17218, v10
	v_exp_f32_e32 v78, v10
	v_fmamk_f32 v10, v64, 0x3c088888, v186
	v_fmaak_f32 v10, v64, v10, 0x3e2aaaab
	v_fma_f32 v10, v64, v10, 0.5
	v_fma_f32 v10, v64, v10, 1.0
	v_mul_f32_e32 v65, v64, v10
	v_add_f32_e32 v10, 1.0, v11
	v_rcp_f32_e32 v10, v10
	v_add_f32_e32 v11, v192, v33
	v_mul_f32_e32 v11, 0xbfb8aa3b, v11
	v_exp_f32_e32 v11, v11
	v_mul_f32_e32 v10, v194, v10
	v_mul_f32_e32 v146, 0x3fb17218, v10
	v_exp_f32_e32 v77, v10
	v_fmamk_f32 v10, v146, 0x3c088888, v186
	v_fmaak_f32 v10, v146, v10, 0x3e2aaaab
	v_fma_f32 v10, v146, v10, 0.5
	v_fma_f32 v10, v146, v10, 1.0
	v_mul_f32_e32 v147, v146, v10
	v_add_f32_e32 v10, 1.0, v11
	v_rcp_f32_e32 v10, v10
	v_fma_f32 v24, v75, v75, -1.0
	v_mul_f32_e32 v209, v19, v9
	v_mul_f32_e32 v10, v194, v10
	v_mul_f32_e32 v156, 0x3fb17218, v10
	v_add_f32_e32 v19, 1.0, v21
	v_cmp_lt_f32_e32 vcc, s76, v22
	v_exp_f32_e32 v79, v10
	v_fmamk_f32 v10, v156, 0x3c088888, v186
	v_rcp_f32_e32 v35, v19
	v_cndmask_b32_e32 v19, v24, v23, vcc
	v_fmaak_f32 v10, v156, v10, 0x3e2aaaab
	v_sqrt_f32_e64 v36, -v19
	v_fma_f32 v10, v156, v10, 0.5
	v_fma_f32 v10, v156, v10, 1.0
	s_waitcnt lgkmcnt(0)
; __device__ __forceinline__ float bf2f(bf16_t b) { return __uint_as_float(((unsigned)b) << 16); }
; __device__ __forceinline__ float fast_sigmoid(float x) { return __builtin_amdgcn_rcpf(1.0f + __builtin_amdgcn_exp2f(-1.4426950408889634f * x)); }
; template <int DIR>
; __device__ __forceinline__ void scan_dir(PP p, const bf16_t* xs, const ScanW& w, ScanW& wn, int ndir, int nct, bool do_next, int n, int ct, int l31, int hl, int id, int rowbase, bool latent, float (&hf)[2][16]) {
;     ...
;     for (int rt = 0; rt < 2; ++rt) {
;         bf16x8 af[4];
; #pragma unroll
;         for (int st = 0; st < 4; ++st) af[st] = *(const bf16x8*)(xs + (32 * rt + l31) * XS + 64 * n + 16 * st + 8 * hl);
;         f32x16 ga, gi;
; #pragma unroll
;         for (int i = 0; i < 16; ++i) { ga[i] = 0.f; gi[i] = 0.f; }
; #pragma unroll
;         for (int st = 0; st < 4; ++st) { ga = __builtin_amdgcn_mfma_f32_32x32x16_bf16(af[st], wfa[st], ga, 0, 0, 0); gi = __builtin_amdgcn_mfma_f32_32x32x16_bf16(af[st], wfi[st], gi, 0, 0, 0); }
; #pragma unroll
;         for (int i = 0; i < 16; ++i) {
;             const int token = 32 * rt + 8 * (i >> 2) + 4 * hl + (i & 3);
;             const float xv = bf2f(xs[token * XS + ch]);
;             const float rr = fast_sigmoid(ga[i] + ba), ii = fast_sigmoid(gi[i] + bi);
;             const float la2 = rr * sp8l2;
;             const float av = __builtin_amdgcn_exp2f(la2);
;             const float t2 = la2 * 1.3862943611f;
;             float em1p = t2 * (1.0f + t2 * (0.5f + t2 * (0.16666667f + t2 * (0.041666668f + t2 * 0.0083333333f)))), em1e = __builtin_fmaf(av, av, -1.0f);
;             asm volatile("" : "+v"(em1p), "+v"(em1e));
;             const float em1 = (t2 > -0.1f) ? em1p : em1e;
;             a[rt][i] = av; u[rt][i] = __builtin_amdgcn_sqrtf(-em1) * (ii * xv);
;         }
	v_lshlrev_b32_e32 v9, 16, v92
	v_fma_f32 v62, v72, v72, -1.0
	v_fma_f32 v80, v78, v78, -1.0
	v_fma_f32 v154, v77, v77, -1.0
	v_mul_f32_e32 v158, v156, v10
	v_fma_f32 v159, v79, v79, -1.0
	v_mul_f32_e32 v9, v35, v9
	ds_read_u16 v34, v18 offset:16640
	ds_read_u16 v63, v0 offset:26000
	ds_read_u16 v81, v0 offset:27040
	ds_read_u16 v155, v0 offset:28080
	ds_read_b128 v[10:13], v187 offset:33280
	ds_read_u16 v195, v18 offset:24960
	v_mul_f32_e32 v217, v36, v9
	v_add_f32_e32 v9, v191, v14
	v_mul_f32_e32 v9, 0xbfb8aa3b, v9
	v_exp_f32_e32 v9, v9
	v_add_f32_e32 v15, v191, v15
	v_mul_f32_e32 v15, 0xbfb8aa3b, v15
	v_exp_f32_e32 v15, v15
	v_add_f32_e32 v9, 1.0, v9
	v_rcp_f32_e32 v9, v9
	ds_read_b128 v[56:59], v187 offset:33312
	s_waitcnt lgkmcnt(6)
	v_lshlrev_b32_e32 v14, 16, v34
	s_waitcnt lgkmcnt(2)
	v_mfma_f32_32x32x16_bf16 v[34:49], v[10:13], v[134:137], 0
	v_cmp_lt_f32_e32 vcc, s76, v60
	v_mul_f32_e32 v9, v9, v14
	v_add_f32_e32 v14, 1.0, v15
	v_rcp_f32_e32 v14, v14
	v_mfma_f32_32x32x16_bf16 v[18:33], v[10:13], v[114:117], 0
	v_cndmask_b32_e32 v10, v62, v61, vcc
	v_sqrt_f32_e64 v60, -v10
	ds_read_b128 v[10:13], v187 offset:33344
	v_cmp_lt_f32_e32 vcc, s76, v64
	v_mul_f32_e32 v197, v60, v9
	v_lshlrev_b32_e32 v9, 16, v63
	v_mul_f32_e32 v9, v14, v9
	v_add_f32_e32 v14, v191, v16
	s_waitcnt lgkmcnt(1)
	v_mfma_f32_32x32x16_bf16 v[34:49], v[56:59], v[126:129], v[34:49]
	v_mul_f32_e32 v14, 0xbfb8aa3b, v14
	v_exp_f32_e32 v14, v14
	v_cndmask_b32_e32 v15, v80, v65, vcc
	v_sqrt_f32_e64 v15, -v15
	v_cmp_lt_f32_e32 vcc, s76, v146
	v_add_f32_e32 v14, 1.0, v14
	v_mul_f32_e32 v199, v15, v9
	v_mfma_f32_32x32x16_bf16 v[18:33], v[56:59], v[118:121], v[18:33]
	v_rcp_f32_e32 v56, v14
	v_add_f32_e32 v14, v191, v17
	v_mul_f32_e32 v57, 0xbfb8aa3b, v14
	ds_read_b128 v[14:17], v187 offset:33376
	v_lshlrev_b32_e32 v9, 16, v81
	v_mul_f32_e32 v9, v56, v9
	s_waitcnt lgkmcnt(1)
	v_mfma_f32_32x32x16_bf16 v[34:49], v[10:13], v[130:133], v[34:49]
	v_mfma_f32_32x32x16_bf16 v[18:33], v[10:13], v[122:125], v[18:33]
	v_exp_f32_e32 v10, v57
	v_cndmask_b32_e32 v11, v154, v147, vcc
	v_sqrt_f32_e64 v11, -v11
	v_cmp_lt_f32_e32 vcc, s76, v156
	v_add_f32_e32 v10, 1.0, v10
	v_rcp_f32_e32 v10, v10
	v_cndmask_b32_e32 v12, v159, v158, vcc
	s_waitcnt lgkmcnt(0)
	v_mfma_f32_32x32x16_bf16 v[34:49], v[14:17], v[142:145], v[34:49]
	v_sqrt_f32_e64 v12, -v12
	v_mul_f32_e32 v204, v11, v9
	v_lshlrev_b32_e32 v9, 16, v155
	v_mul_f32_e32 v9, v10, v9
	v_mul_f32_e32 v202, v12, v9
	v_lshlrev_b32_e32 v11, 16, v195
	s_nop 5
	v_add_f32_e32 v10, v191, v34
	v_mfma_f32_32x32x16_bf16 v[18:33], v[14:17], v[138:141], v[18:33]
	v_mul_f32_e32 v10, 0xbfb8aa3b, v10
	v_exp_f32_e32 v10, v10
	s_nop 0
	v_add_f32_e32 v10, 1.0, v10
	v_rcp_f32_e32 v10, v10
	s_nop 6
	v_add_f32_e32 v9, v192, v18
	v_mul_f32_e32 v9, 0xbfb8aa3b, v9
	v_exp_f32_e32 v9, v9
	v_mul_f32_e32 v10, v10, v11
	v_add_f32_e32 v11, v192, v19
	v_mul_f32_e32 v11, 0xbfb8aa3b, v11
	v_add_f32_e32 v9, 1.0, v9
	v_rcp_f32_e32 v9, v9
	v_exp_f32_e32 v11, v11
	v_mul_f32_e32 v9, v194, v9
	v_exp_f32_e32 v80, v9
	v_mul_f32_e32 v9, 0x3fb17218, v9
	v_fmamk_f32 v12, v9, 0x3c088888, v186
	v_fmaak_f32 v12, v9, v12, 0x3e2aaaab
	v_add_f32_e32 v11, 1.0, v11
	v_fma_f32 v12, v9, v12, 0.5
	v_rcp_f32_e32 v11, v11
	v_fma_f32 v12, v9, v12, 1.0
	v_mul_f32_e32 v12, v9, v12
	v_fma_f32 v13, v80, v80, -1.0
	v_cmp_lt_f32_e32 vcc, s76, v9
	v_mul_f32_e32 v11, v194, v11
	v_exp_f32_e32 v146, v11
	v_cndmask_b32_e32 v9, v13, v12, vcc
	v_add_f32_e32 v12, v191, v35
	v_mul_f32_e32 v12, 0xbfb8aa3b, v12
	v_mul_f32_e32 v11, 0x3fb17218, v11
	v_exp_f32_e32 v12, v12
	v_fmamk_f32 v14, v11, 0x3c088888, v186
	v_fmaak_f32 v14, v11, v14, 0x3e2aaaab
	v_fma_f32 v14, v11, v14, 0.5
	v_fma_f32 v14, v11, v14, 1.0
	v_sqrt_f32_e64 v9, -v9
	v_add_f32_e32 v12, 1.0, v12
	v_mul_f32_e32 v14, v11, v14
	v_fma_f32 v15, v146, v146, -1.0
	v_cmp_lt_f32_e32 vcc, s76, v11
	v_rcp_f32_e32 v12, v12
	v_mul_f32_e32 v196, v10, v9
	v_cndmask_b32_e32 v11, v15, v14, vcc
	v_sqrt_f32_e64 v11, -v11
	s_waitcnt lgkmcnt(0)
	v_lshlrev_b32_e32 v9, 16, v93
	v_mul_f32_e32 v9, v12, v9
	v_add_f32_e32 v10, v192, v20
	v_mul_f32_e32 v195, v9, v11
	v_add_f32_e32 v11, v191, v36
	v_mul_f32_e32 v11, 0xbfb8aa3b, v11
	v_exp_f32_e32 v11, v11
	v_mul_f32_e32 v10, 0xbfb8aa3b, v10
	v_exp_f32_e32 v10, v10
	v_add_f32_e32 v11, 1.0, v11
	v_rcp_f32_e32 v11, v11
	v_add_f32_e32 v10, 1.0, v10
	v_rcp_f32_e32 v10, v10
	s_waitcnt lgkmcnt(0)
	v_lshlrev_b32_e32 v9, 16, v94
	v_mul_f32_e32 v9, v11, v9
	v_add_f32_e32 v11, v192, v21
	v_mul_f32_e32 v11, 0xbfb8aa3b, v11
	v_exp_f32_e32 v11, v11
	v_mul_f32_e32 v10, v194, v10
	v_exp_f32_e32 v81, v10
	v_mul_f32_e32 v10, 0x3fb17218, v10
	v_fmamk_f32 v12, v10, 0x3c088888, v186
	v_fmaak_f32 v12, v10, v12, 0x3e2aaaab
	v_add_f32_e32 v11, 1.0, v11
	v_fma_f32 v12, v10, v12, 0.5
	v_rcp_f32_e32 v11, v11
	v_fma_f32 v12, v10, v12, 1.0
	v_mul_f32_e32 v12, v10, v12
	v_fma_f32 v13, v81, v81, -1.0
	v_cmp_lt_f32_e32 vcc, s76, v10
	v_mul_f32_e32 v11, v194, v11
	v_exp_f32_e32 v198, v11
	v_cndmask_b32_e32 v10, v13, v12, vcc
	v_add_f32_e32 v12, v191, v37
	v_mul_f32_e32 v12, 0xbfb8aa3b, v12
	v_mul_f32_e32 v11, 0x3fb17218, v11
	v_exp_f32_e32 v12, v12
	v_fmamk_f32 v14, v11, 0x3c088888, v186
	v_fmaak_f32 v14, v11, v14, 0x3e2aaaab
	v_fma_f32 v14, v11, v14, 0.5
	v_fma_f32 v14, v11, v14, 1.0
	v_sqrt_f32_e64 v10, -v10
	v_add_f32_e32 v12, 1.0, v12
	v_mul_f32_e32 v14, v11, v14
	v_fma_f32 v15, v198, v198, -1.0
	v_cmp_lt_f32_e32 vcc, s76, v11
	v_rcp_f32_e32 v12, v12
	v_mul_f32_e32 v214, v9, v10
	v_cndmask_b32_e32 v11, v15, v14, vcc
	v_sqrt_f32_e64 v11, -v11
	s_waitcnt lgkmcnt(0)
; __device__ __forceinline__ float bf2f(bf16_t b) { return __uint_as_float(((unsigned)b) << 16); }
; __device__ __forceinline__ float fast_sigmoid(float x) { return __builtin_amdgcn_rcpf(1.0f + __builtin_amdgcn_exp2f(-1.4426950408889634f * x)); }
; template <int DIR>
; __device__ __forceinline__ void scan_dir(PP p, const bf16_t* xs, const ScanW& w, ScanW& wn, int ndir, int nct, bool do_next, int n, int ct, int l31, int hl, int id, int rowbase, bool latent, float (&hf)[2][16]) {
;     ...
; #pragma unroll
;         for (int i = 0; i < 16; ++i) {
;             const int token = 32 * rt + 8 * (i >> 2) + 4 * hl + (i & 3);
;             const float xv = bf2f(xs[token * XS + ch]);
;             const float rr = fast_sigmoid(ga[i] + ba), ii = fast_sigmoid(gi[i] + bi);
;             const float la2 = rr * sp8l2;
;             const float av = __builtin_amdgcn_exp2f(la2);
;             const float t2 = la2 * 1.3862943611f;
;             float em1p = t2 * (1.0f + t2 * (0.5f + t2 * (0.16666667f + t2 * (0.041666668f + t2 * 0.0083333333f)))), em1e = __builtin_fmaf(av, av, -1.0f);
;             asm volatile("" : "+v"(em1p), "+v"(em1e));
;             const float em1 = (t2 > -0.1f) ? em1p : em1e;
;             a[rt][i] = av; u[rt][i] = __builtin_amdgcn_sqrtf(-em1) * (ii * xv);
;         }
	v_lshlrev_b32_e32 v9, 16, v95
	v_mul_f32_e32 v9, v12, v9
	v_add_f32_e32 v10, v192, v22
	v_mul_f32_e32 v211, v11, v9
	v_add_f32_e32 v11, v191, v38
	v_mul_f32_e32 v11, 0xbfb8aa3b, v11
	v_exp_f32_e32 v11, v11
	v_mul_f32_e32 v10, 0xbfb8aa3b, v10
	v_exp_f32_e32 v10, v10
	v_add_f32_e32 v11, 1.0, v11
	v_rcp_f32_e32 v11, v11
	v_add_f32_e32 v10, 1.0, v10
	v_rcp_f32_e32 v10, v10
	s_waitcnt lgkmcnt(0)
	v_lshlrev_b32_e32 v9, 16, v96
	v_mul_f32_e32 v9, v11, v9
	v_add_f32_e32 v11, v192, v23
	v_mul_f32_e32 v11, 0xbfb8aa3b, v11
	v_exp_f32_e32 v11, v11
	v_mul_f32_e32 v10, v194, v10
	v_exp_f32_e32 v147, v10
	v_mul_f32_e32 v10, 0x3fb17218, v10
	v_fmamk_f32 v12, v10, 0x3c088888, v186
	v_fmaak_f32 v12, v10, v12, 0x3e2aaaab
	v_add_f32_e32 v11, 1.0, v11
	v_fma_f32 v12, v10, v12, 0.5
	v_rcp_f32_e32 v11, v11
	v_fma_f32 v12, v10, v12, 1.0
	v_mul_f32_e32 v12, v10, v12
	v_fma_f32 v13, v147, v147, -1.0
	v_cmp_lt_f32_e32 vcc, s76, v10
	v_mul_f32_e32 v11, v194, v11
	v_exp_f32_e32 v201, v11
	v_cndmask_b32_e32 v10, v13, v12, vcc
	v_add_f32_e32 v12, v191, v39
	v_mul_f32_e32 v12, 0xbfb8aa3b, v12
	v_mul_f32_e32 v11, 0x3fb17218, v11
	v_exp_f32_e32 v12, v12
	v_fmamk_f32 v14, v11, 0x3c088888, v186
	v_fmaak_f32 v14, v11, v14, 0x3e2aaaab
	v_fma_f32 v14, v11, v14, 0.5
	v_fma_f32 v14, v11, v14, 1.0
	v_sqrt_f32_e64 v10, -v10
	v_add_f32_e32 v12, 1.0, v12
	v_mul_f32_e32 v14, v11, v14
	v_fma_f32 v15, v201, v201, -1.0
	v_cmp_lt_f32_e32 vcc, s76, v11
	v_rcp_f32_e32 v12, v12
	v_mul_f32_e32 v206, v10, v9
	v_cndmask_b32_e32 v11, v15, v14, vcc
	v_sqrt_f32_e64 v11, -v11
	s_waitcnt lgkmcnt(0)
	v_lshlrev_b32_e32 v9, 16, v97
	v_mul_f32_e32 v9, v12, v9
	v_add_f32_e32 v10, v192, v24
	v_mul_f32_e32 v205, v11, v9
	v_add_f32_e32 v11, v191, v40
	v_mul_f32_e32 v11, 0xbfb8aa3b, v11
	v_exp_f32_e32 v11, v11
	v_mul_f32_e32 v10, 0xbfb8aa3b, v10
	v_exp_f32_e32 v10, v10
	v_add_f32_e32 v11, 1.0, v11
	v_rcp_f32_e32 v11, v11
	v_add_f32_e32 v10, 1.0, v10
	v_rcp_f32_e32 v10, v10
	s_waitcnt lgkmcnt(0)
	v_lshlrev_b32_e32 v9, 16, v98
	v_mul_f32_e32 v9, v11, v9
	v_add_f32_e32 v11, v192, v25
	v_mul_f32_e32 v11, 0xbfb8aa3b, v11
	v_exp_f32_e32 v11, v11
	v_mul_f32_e32 v10, v194, v10
	v_exp_f32_e32 v200, v10
	v_mul_f32_e32 v10, 0x3fb17218, v10
	v_fmamk_f32 v12, v10, 0x3c088888, v186
	v_fmaak_f32 v12, v10, v12, 0x3e2aaaab
	v_add_f32_e32 v11, 1.0, v11
	v_fma_f32 v12, v10, v12, 0.5
	v_rcp_f32_e32 v11, v11
	v_fma_f32 v12, v10, v12, 1.0
	v_mul_f32_e32 v12, v10, v12
	v_fma_f32 v13, v200, v200, -1.0
	v_cmp_lt_f32_e32 vcc, s76, v10
	v_mul_f32_e32 v11, v194, v11
	v_exp_f32_e32 v207, v11
	v_cndmask_b32_e32 v10, v13, v12, vcc
	v_add_f32_e32 v12, v191, v41
	v_mul_f32_e32 v12, 0xbfb8aa3b, v12
	v_mul_f32_e32 v11, 0x3fb17218, v11
	v_exp_f32_e32 v12, v12
	v_fmamk_f32 v14, v11, 0x3c088888, v186
	v_fmaak_f32 v14, v11, v14, 0x3e2aaaab
	v_fma_f32 v14, v11, v14, 0.5
	v_fma_f32 v14, v11, v14, 1.0
	v_sqrt_f32_e64 v10, -v10
	v_add_f32_e32 v12, 1.0, v12
	v_mul_f32_e32 v14, v11, v14
	v_fma_f32 v15, v207, v207, -1.0
	v_cmp_lt_f32_e32 vcc, s76, v11
	v_rcp_f32_e32 v12, v12
	v_mul_f32_e32 v222, v10, v9
	v_cndmask_b32_e32 v11, v15, v14, vcc
	v_sqrt_f32_e64 v11, -v11
	s_waitcnt lgkmcnt(0)
	v_lshlrev_b32_e32 v9, 16, v99
	v_mul_f32_e32 v9, v12, v9
	v_add_f32_e32 v10, v192, v26
	v_mul_f32_e32 v221, v11, v9
	v_add_f32_e32 v11, v191, v42
	v_mul_f32_e32 v11, 0xbfb8aa3b, v11
	v_exp_f32_e32 v11, v11
	v_mul_f32_e32 v10, 0xbfb8aa3b, v10
	v_exp_f32_e32 v10, v10
	v_add_f32_e32 v11, 1.0, v11
	v_rcp_f32_e32 v11, v11
	v_add_f32_e32 v10, 1.0, v10
	v_rcp_f32_e32 v10, v10
	s_waitcnt lgkmcnt(0)
	v_lshlrev_b32_e32 v9, 16, v100
	v_mul_f32_e32 v9, v11, v9
	v_add_f32_e32 v11, v192, v27
	v_mul_f32_e32 v11, 0xbfb8aa3b, v11
	v_exp_f32_e32 v11, v11
	v_mul_f32_e32 v10, v194, v10
	v_exp_f32_e32 v203, v10
	v_mul_f32_e32 v10, 0x3fb17218, v10
	v_fmamk_f32 v12, v10, 0x3c088888, v186
	v_fmaak_f32 v12, v10, v12, 0x3e2aaaab
	v_add_f32_e32 v11, 1.0, v11
	v_fma_f32 v12, v10, v12, 0.5
	v_rcp_f32_e32 v11, v11
	v_fma_f32 v12, v10, v12, 1.0
	v_mul_f32_e32 v12, v10, v12
	v_fma_f32 v13, v203, v203, -1.0
	v_cmp_lt_f32_e32 vcc, s76, v10
	v_mul_f32_e32 v11, v194, v11
	v_exp_f32_e32 v210, v11
	v_cndmask_b32_e32 v10, v13, v12, vcc
	v_add_f32_e32 v12, v191, v43
	v_mul_f32_e32 v12, 0xbfb8aa3b, v12
	v_mul_f32_e32 v11, 0x3fb17218, v11
	v_exp_f32_e32 v12, v12
	v_fmamk_f32 v14, v11, 0x3c088888, v186
	v_fmaak_f32 v14, v11, v14, 0x3e2aaaab
	v_fma_f32 v14, v11, v14, 0.5
	v_fma_f32 v14, v11, v14, 1.0
	v_sqrt_f32_e64 v10, -v10
	v_add_f32_e32 v12, 1.0, v12
	v_mul_f32_e32 v14, v11, v14
	v_fma_f32 v15, v210, v210, -1.0
	v_cmp_lt_f32_e32 vcc, s76, v11
	v_rcp_f32_e32 v12, v12
	v_mul_f32_e32 v216, v10, v9
	v_cndmask_b32_e32 v11, v15, v14, vcc
	v_sqrt_f32_e64 v11, -v11
	s_waitcnt lgkmcnt(0)
	v_lshlrev_b32_e32 v9, 16, v101
	v_mul_f32_e32 v9, v12, v9
	v_add_f32_e32 v10, v192, v28
	v_mul_f32_e32 v215, v11, v9
	v_add_f32_e32 v11, v191, v44
	v_mul_f32_e32 v11, 0xbfb8aa3b, v11
	v_exp_f32_e32 v11, v11
	v_mul_f32_e32 v10, 0xbfb8aa3b, v10
	v_exp_f32_e32 v10, v10
	v_add_f32_e32 v11, 1.0, v11
	v_rcp_f32_e32 v11, v11
	v_add_f32_e32 v10, 1.0, v10
	v_rcp_f32_e32 v10, v10
	s_waitcnt lgkmcnt(0)
; __device__ __forceinline__ float bf2f(bf16_t b) { return __uint_as_float(((unsigned)b) << 16); }
; __device__ __forceinline__ float fast_sigmoid(float x) { return __builtin_amdgcn_rcpf(1.0f + __builtin_amdgcn_exp2f(-1.4426950408889634f * x)); }
; template <int DIR>
; __device__ __forceinline__ void scan_dir(PP p, const bf16_t* xs, const ScanW& w, ScanW& wn, int ndir, int nct, bool do_next, int n, int ct, int l31, int hl, int id, int rowbase, bool latent, float (&hf)[2][16]) {
;     ...
; #pragma unroll
;         for (int i = 0; i < 16; ++i) {
;             const int token = 32 * rt + 8 * (i >> 2) + 4 * hl + (i & 3);
;             const float xv = bf2f(xs[token * XS + ch]);
;             const float rr = fast_sigmoid(ga[i] + ba), ii = fast_sigmoid(gi[i] + bi);
;             const float la2 = rr * sp8l2;
;             const float av = __builtin_amdgcn_exp2f(la2);
;             const float t2 = la2 * 1.3862943611f;
;             float em1p = t2 * (1.0f + t2 * (0.5f + t2 * (0.16666667f + t2 * (0.041666668f + t2 * 0.0083333333f)))), em1e = __builtin_fmaf(av, av, -1.0f);
;             asm volatile("" : "+v"(em1p), "+v"(em1e));
;             const float em1 = (t2 > -0.1f) ? em1p : em1e;
;             a[rt][i] = av; u[rt][i] = __builtin_amdgcn_sqrtf(-em1) * (ii * xv);
;         }
;     }
;     float Ao[8], Ho[8], Ap[8], Hp[8];
; #pragma unroll
;     for (int k = 0; k < 8; ++k) {
;         const int rt = k >> 2, g = k & 3;
;         float H = 0.f, A = 1.f;
; #pragma unroll
;         for (int jj = 0; jj < 4; ++jj) { const int j = DIR ? 3 - jj : jj; const float av = a[rt][4 * g + j]; H = av * H + u[rt][4 * g + j]; A *= av; }
;         Ao[k] = A; Ho[k] = H; Ap[k] = __shfl_xor(A, 32); Hp[k] = __shfl_xor(H, 32);
;     }
;     ...
;     if (do_next) scan_loadw(p, ndir, n, nct, l31, hl, wn);
	v_lshlrev_b32_e32 v9, 16, v102
	v_mul_f32_e32 v9, v11, v9
	v_add_f32_e32 v11, v192, v29
	v_mul_f32_e32 v11, 0xbfb8aa3b, v11
	v_exp_f32_e32 v11, v11
	v_mul_f32_e32 v10, v194, v10
	v_exp_f32_e32 v208, v10
	v_mul_f32_e32 v10, 0x3fb17218, v10
	v_fmamk_f32 v12, v10, 0x3c088888, v186
	v_fmaak_f32 v12, v10, v12, 0x3e2aaaab
	v_add_f32_e32 v11, 1.0, v11
	v_fma_f32 v12, v10, v12, 0.5
	v_rcp_f32_e32 v11, v11
	v_fma_f32 v12, v10, v12, 1.0
	v_mul_f32_e32 v12, v10, v12
	v_fma_f32 v13, v208, v208, -1.0
	v_cmp_lt_f32_e32 vcc, s76, v10
	v_mul_f32_e32 v11, v194, v11
	v_exp_f32_e32 v218, v11
	v_cndmask_b32_e32 v10, v13, v12, vcc
	v_add_f32_e32 v12, v191, v45
	v_mul_f32_e32 v12, 0xbfb8aa3b, v12
	v_mul_f32_e32 v11, 0x3fb17218, v11
	v_exp_f32_e32 v12, v12
	v_fmamk_f32 v14, v11, 0x3c088888, v186
	v_fmaak_f32 v14, v11, v14, 0x3e2aaaab
	v_fma_f32 v14, v11, v14, 0.5
	v_fma_f32 v14, v11, v14, 1.0
	v_sqrt_f32_e64 v10, -v10
	v_add_f32_e32 v12, 1.0, v12
	v_mul_f32_e32 v14, v11, v14
	v_fma_f32 v15, v218, v218, -1.0
	v_cmp_lt_f32_e32 vcc, s76, v11
	v_rcp_f32_e32 v12, v12
	v_mul_f32_e32 v227, v10, v9
	v_cndmask_b32_e32 v11, v15, v14, vcc
	v_sqrt_f32_e64 v11, -v11
	s_waitcnt lgkmcnt(0)
	v_lshlrev_b32_e32 v9, 16, v103
	v_mul_f32_e32 v9, v12, v9
	v_add_f32_e32 v10, v192, v30
	v_mul_f32_e32 v226, v11, v9
	v_add_f32_e32 v11, v191, v46
	v_mul_f32_e32 v11, 0xbfb8aa3b, v11
	v_exp_f32_e32 v11, v11
	v_mul_f32_e32 v10, 0xbfb8aa3b, v10
	v_exp_f32_e32 v10, v10
	v_add_f32_e32 v11, 1.0, v11
	v_rcp_f32_e32 v11, v11
	v_add_f32_e32 v10, 1.0, v10
	v_rcp_f32_e32 v10, v10
	s_waitcnt lgkmcnt(0)
	v_lshlrev_b32_e32 v9, 16, v104
	v_mul_f32_e32 v9, v11, v9
	v_add_f32_e32 v11, v192, v31
	v_mul_f32_e32 v11, 0xbfb8aa3b, v11
	v_exp_f32_e32 v11, v11
	v_mul_f32_e32 v10, v194, v10
	v_exp_f32_e32 v213, v10
	v_mul_f32_e32 v10, 0x3fb17218, v10
	v_fmamk_f32 v12, v10, 0x3c088888, v186
	v_fmaak_f32 v12, v10, v12, 0x3e2aaaab
	v_add_f32_e32 v11, 1.0, v11
	v_fma_f32 v12, v10, v12, 0.5
	v_rcp_f32_e32 v11, v11
	v_fma_f32 v12, v10, v12, 1.0
	v_mul_f32_e32 v12, v10, v12
	v_fma_f32 v13, v213, v213, -1.0
	v_cmp_lt_f32_e32 vcc, s76, v10
	v_mul_f32_e32 v11, v194, v11
	v_exp_f32_e32 v220, v11
	v_cndmask_b32_e32 v10, v13, v12, vcc
	v_add_f32_e32 v12, v191, v47
	v_mul_f32_e32 v12, 0xbfb8aa3b, v12
	v_mul_f32_e32 v11, 0x3fb17218, v11
	v_exp_f32_e32 v12, v12
	v_fmamk_f32 v14, v11, 0x3c088888, v186
	v_fmaak_f32 v14, v11, v14, 0x3e2aaaab
	v_fma_f32 v14, v11, v14, 0.5
	v_fma_f32 v14, v11, v14, 1.0
	v_sqrt_f32_e64 v10, -v10
	v_add_f32_e32 v12, 1.0, v12
	v_mul_f32_e32 v14, v11, v14
	v_fma_f32 v15, v220, v220, -1.0
	v_cmp_lt_f32_e32 vcc, s76, v11
	v_rcp_f32_e32 v12, v12
	v_mul_f32_e32 v224, v10, v9
	v_cndmask_b32_e32 v11, v15, v14, vcc
	v_sqrt_f32_e64 v11, -v11
	s_waitcnt lgkmcnt(0)
	v_lshlrev_b32_e32 v9, 16, v105
	v_mul_f32_e32 v9, v12, v9
	v_add_f32_e32 v10, v192, v32
	v_mul_f32_e32 v223, v11, v9
	v_add_f32_e32 v11, v191, v48
	v_mul_f32_e32 v11, 0xbfb8aa3b, v11
	v_exp_f32_e32 v11, v11
	v_mul_f32_e32 v10, 0xbfb8aa3b, v10
	v_exp_f32_e32 v10, v10
	v_add_f32_e32 v11, 1.0, v11
	v_rcp_f32_e32 v11, v11
	v_add_f32_e32 v10, 1.0, v10
	v_rcp_f32_e32 v10, v10
	s_waitcnt lgkmcnt(0)
	v_lshlrev_b32_e32 v9, 16, v106
	v_mul_f32_e32 v9, v11, v9
	v_add_f32_e32 v11, v192, v33
	v_mul_f32_e32 v11, 0xbfb8aa3b, v11
	v_exp_f32_e32 v11, v11
	v_mul_f32_e32 v10, v194, v10
	v_exp_f32_e32 v219, v10
	v_mul_f32_e32 v10, 0x3fb17218, v10
	v_fmamk_f32 v12, v10, 0x3c088888, v186
	v_fmaak_f32 v12, v10, v12, 0x3e2aaaab
	v_add_f32_e32 v11, 1.0, v11
	v_fma_f32 v12, v10, v12, 0.5
	v_rcp_f32_e32 v11, v11
	v_fma_f32 v12, v10, v12, 1.0
	v_mul_f32_e32 v12, v10, v12
	v_fma_f32 v13, v219, v219, -1.0
	v_cmp_lt_f32_e32 vcc, s76, v10
	v_mul_f32_e32 v11, v194, v11
	v_exp_f32_e32 v225, v11
	v_cndmask_b32_e32 v10, v13, v12, vcc
	v_add_f32_e32 v12, v191, v49
	v_mul_f32_e32 v12, 0xbfb8aa3b, v12
	v_mul_f32_e32 v11, 0x3fb17218, v11
	v_exp_f32_e32 v12, v12
	v_fmamk_f32 v13, v11, 0x3c088888, v186
	v_fmaak_f32 v13, v11, v13, 0x3e2aaaab
	v_fma_f32 v13, v11, v13, 0.5
	ds_read_u16 v0, v0 offset:61360
	v_fma_f32 v13, v11, v13, 1.0
	v_add_f32_e32 v12, 1.0, v12
	v_mul_f32_e32 v13, v11, v13
	v_fma_f32 v14, v225, v225, -1.0
	v_cmp_lt_f32_e32 vcc, s76, v11
	v_sqrt_f32_e64 v10, -v10
	v_rcp_f32_e32 v12, v12
	s_waitcnt lgkmcnt(0)
	v_lshlrev_b32_e32 v0, 16, v0
	v_cndmask_b32_e32 v11, v14, v13, vcc
	v_sqrt_f32_e64 v11, -v11
	v_mul_f32_e32 v229, v10, v9
	v_mul_f32_e32 v0, v12, v0
	v_and_b32_e32 v9, 64, v188
	v_mul_f32_e32 v228, v11, v0
	v_xor_b32_e32 v0, 32, v188
	v_add_u32_e32 v9, 64, v9
	v_cmp_lt_i32_e32 vcc, v0, v9
	v_fma_f32 v9, 0, v50, v2
	v_fma_f32 v9, v52, v9, v3
	v_fma_f32 v9, v51, v9, v4
	v_fma_f32 v34, v54, v9, v5
	v_fma_f32 v9, 0, v53, v6
	v_fma_f32 v9, v55, v9, v7
	v_fma_f32 v9, v67, v9, v8
	v_fma_f32 v255, v69, v9, v76
	v_fma_f32 v9, 0, v68, v74
	v_fma_f32 v9, v71, v9, v73
	v_mul_f32_e32 v10, v50, v52
	v_fma_f32 v9, v70, v9, v209
	v_mul_f32_e32 v10, v51, v10
	v_fma_f32 v251, v75, v9, v217
	v_fma_f32 v9, 0, v72, v197
	v_mul_f32_e32 v35, v54, v10
	v_mul_f32_e32 v10, v53, v55
	v_fma_f32 v9, v78, v9, v199
	v_mul_f32_e32 v10, v67, v10
	v_fma_f32 v9, v77, v9, v204
	v_mul_f32_e32 v154, v69, v10
	v_mul_f32_e32 v10, v68, v71
	v_fma_f32 v247, v79, v9, v202
	v_fma_f32 v9, 0, v80, v196
	v_mul_f32_e32 v10, v70, v10
	v_fma_f32 v9, v146, v9, v195
	v_mul_f32_e32 v253, v75, v10
	v_mul_f32_e32 v10, v72, v78
	v_fma_f32 v9, v81, v9, v214
	v_mul_f32_e32 v10, v77, v10
	v_fma_f32 v243, v198, v9, v211
	v_fma_f32 v9, 0, v147, v206
	v_mul_f32_e32 v249, v79, v10
	v_mul_f32_e32 v10, v80, v146
	v_fma_f32 v9, v201, v9, v205
	v_mul_f32_e32 v10, v81, v10
	v_fma_f32 v9, v200, v9, v222
	v_mul_f32_e32 v245, v198, v10
	v_mul_f32_e32 v10, v147, v201
	v_fma_f32 v239, v207, v9, v221
	v_fma_f32 v9, 0, v203, v216
	v_mul_f32_e32 v10, v200, v10
	v_fma_f32 v9, v210, v9, v215
	v_mul_f32_e32 v241, v207, v10
	v_mul_f32_e32 v10, v203, v210
	v_fma_f32 v9, v208, v9, v227
	v_mul_f32_e32 v10, v208, v10
	v_fma_f32 v234, v218, v9, v226
	v_fma_f32 v9, 0, v213, v224
	v_mul_f32_e32 v236, v218, v10
	v_fma_f32 v9, v220, v9, v223
	v_mul_f32_e32 v10, v213, v220
	v_cndmask_b32_e32 v0, v188, v0, vcc
	v_fma_f32 v9, v219, v9, v229
	v_mul_f32_e32 v10, v219, v10
	v_lshlrev_b32_e32 v0, 2, v0
	v_fma_f32 v230, v225, v9, v228
	v_mul_f32_e32 v231, v225, v10
	ds_bpermute_b32 v36, v0, v35
	ds_bpermute_b32 v37, v0, v34
	ds_bpermute_b32 v155, v0, v154
	ds_bpermute_b32 v212, v0, v255
	ds_bpermute_b32 v254, v0, v253
	ds_bpermute_b32 v252, v0, v251
	ds_bpermute_b32 v250, v0, v249
	ds_bpermute_b32 v248, v0, v247
	ds_bpermute_b32 v246, v0, v245
	ds_bpermute_b32 v244, v0, v243
	ds_bpermute_b32 v242, v0, v241
	ds_bpermute_b32 v240, v0, v239
	ds_bpermute_b32 v237, v0, v236
	ds_bpermute_b32 v235, v0, v234
	ds_bpermute_b32 v232, v0, v231
	ds_bpermute_b32 v233, v0, v230
	s_andn2_b64 s[4:5], exec, s[22:23]
	s_andn2_b64 vcc, exec, s[22:23]
	s_cbranch_vccnz .LBB0_380
; __device__ __forceinline__ void scan_loadw(PP p, int dir, int n, int ct, int l31, int hl, ScanW& w) {
;     unsigned chv = (unsigned)(32 * ct + l31); asm volatile("" : "+v"(chv));
;     const unsigned ch = (unsigned)(dir * 512 + 64 * n) + chv;
;     w.ba = p->lru_b_a[ch]; w.bi = p->lru_b_i[ch];
;     w.sp8l2 = ((const float*)(p->ws + WS_SP8))[ch] * 1.4426950408889634f;
;     const bf16_t* wa_b = (const bf16_t*)(p->ws + WS_LRU) + (size_t)((dir * 2 + 0) * 8 + n) * 4096;
;     const bf16_t* wi_b = (const bf16_t*)(p->ws + WS_LRU) + (size_t)((dir * 2 + 1) * 8 + n) * 4096;
;     const unsigned lo = chv * 64u + 8u * (unsigned)hl;
; #pragma unroll
;     for (int st = 0; st < 4; ++st) { w.wfa[st] = *(const bf16x8*)(wa_b + lo + 16 * st); w.wfi[st] = *(const bf16x8*)(wi_b + lo + 16 * st); }
; }
	v_or_b32_e32 v9, s48, v148
	s_load_dwordx2 s[48:49], s[8:9], 0x58
	s_load_dwordx2 s[82:83], s[8:9], 0x68
	v_add_u32_e32 v0, s50, v9
	v_lshlrev_b64 v[10:11], 2, v[0:1]
	v_lshl_or_b32 v0, v9, 6, v149
	s_waitcnt lgkmcnt(0)
	v_lshl_add_u64 v[12:13], s[48:49], 0, v[10:11]
	global_load_dword v189, v[12:13], off
	v_lshl_add_u64 v[12:13], s[82:83], 0, v[10:11]
	global_load_dword v190, v[12:13], off
	v_lshl_add_u64 v[10:11], s[12:13], 0, v[10:11]
	v_lshlrev_b64 v[12:13], 1, v[0:1]
	v_lshl_add_u64 v[14:15], s[20:21], 0, v[12:13]
	v_lshl_add_u64 v[12:13], s[16:17], 0, v[12:13]
	global_load_dword v144, v[10:11], off
	global_load_dwordx4 v[82:85], v[14:15], off
	global_load_dwordx4 v[86:89], v[14:15], off offset:32
	global_load_dwordx4 v[90:93], v[14:15], off offset:64
	global_load_dwordx4 v[94:97], v[12:13], off offset:32
	global_load_dwordx4 v[102:105], v[12:13], off offset:64
	global_load_dwordx4 v[98:101], v[12:13], off
	global_load_dwordx4 v[106:109], v[14:15], off offset:96
	global_load_dwordx4 v[110:113], v[12:13], off offset:96
